# Q prologue batching + s_nop 0 pad to keep the hot loop at its previous 8-byte code phase
# baseline (speedup 1.0000x reference)
.LBB0_397:
	s_and_b32 s45, s0, 15
	s_ashr_i32 s37, s36, 31
	s_mul_i32 s3, s36, 0x1800
	s_mul_hi_i32 s1, s36, 0x1800
	s_add_u32 s3, s78, s3
	v_readlane_b32 s2, v252, 50
	s_addc_u32 s1, s2, s1
	s_lshl_b32 s5, s45, 7
	s_add_u32 s30, s3, s5
	s_addc_u32 s31, s1, 0
	v_readlane_b32 s2, v250, 19
	v_readlane_b32 s3, v250, 20
	s_add_u32 s28, s2, s5
	v_mov_b32_e32 v6, v168
	s_addc_u32 s29, s3, 0
	s_lshl_b32 s0, s0, 7
	s_and_b32 s0, s0, 0x700
	v_ashrrev_i32_e32 v0, 6, v6
	v_and_b32_e32 v62, 63, v6
	v_and_b32_e32 v1, 0x3fffffc0, v6
	v_and_b32_e32 v200, 31, v6
	v_lshl_add_u32 v175, v1, 2, v192
	v_lshl_add_u32 v1, v0, 12, v192
	v_lshlrev_b32_e32 v7, 4, v62
	v_lshlrev_b32_e32 v174, 5, v0
	s_add_u32 s39, s73, s0
	v_bfe_u32 v201, v6, 5, 1
	v_add_u32_e32 v204, v1, v7
	v_or_b32_e32 v2, v174, v200
	v_mov_b64_e32 v[0:1], s[30:31]
	s_movk_i32 s0, 0x1800
	v_mad_i64_i32 v[0:1], s[0:1], v2, s0, v[0:1]
	v_lshlrev_b32_e32 v176, 4, v201
	v_mov_b32_e32 v177, v171
	v_lshl_add_u64 v[4:5], v[0:1], 0, v[176:177]
	global_load_dwordx4 v[28:31], v[4:5], off
	global_load_dwordx4 v[16:19], v[4:5], off offset:32
	global_load_dwordx4 v[20:23], v[4:5], off offset:64
	global_load_dwordx4 v[24:27], v[4:5], off offset:96
	s_nop 0
	v_lshlrev_b32_e32 v12, 3, v6
	s_movk_i32 s1, 0xe0
	s_mov_b32 s0, 0x7ffffc
	s_addc_u32 s42, s63, 0
	s_cmp_lg_u32 0x100, -1
	s_mul_i32 s44, s38, 0x1800
	s_mul_hi_i32 s43, s38, 0x1800
	v_and_b32_e32 v8, 0x70, v6
	v_lshlrev_b32_e32 v72, 7, v200
	v_and_b32_e32 v73, 0x70, v12
	v_or_b32_e32 v64, 32, v176
	v_bitop3_b32 v64, v64, v72, v73 bitop3:0xde
	v_add_u32_e32 v209, 0x100, v64
	s_mov_b32 s5, s4
	s_mov_b32 s10, s4
	s_mov_b32 s11, s4
	s_mov_b32 s12, s4
	s_mov_b32 s13, s4
	s_mov_b32 s14, s4
	s_mov_b32 s15, s4
	s_mov_b32 s16, s4
	s_mov_b32 s17, s4
	s_mov_b32 s18, s4
	s_mov_b32 s19, s4
	v_mov_b32_e32 v61, v171
	v_cmp_gt_u32_e64 s[40:41], 32, v62
	s_mov_b32 s50, 4
	s_movk_i32 s51, 0xc0
	v_lshl_add_u32 v177, v200, 2, v175
	v_mov_b32_e32 v178, 0
	v_and_b32_e32 v5, 24, v12
	v_ashrrev_i32_e32 v0, 4, v6
	v_lshlrev_b32_e32 v4, 5, v0
	v_lshrrev_b32_e32 v2, 5, v6
	v_bfe_u32 v3, v12, 5, 2
	v_and_or_b32 v4, v4, s1, v5
	v_and_or_b32 v2, v2, s0, v3
	v_lshlrev_b32_e32 v4, 1, v4
	v_lshl_or_b32 v13, v2, 9, v4
	v_add_u32_e32 v2, 32, v0
	v_lshrrev_b32_e32 v2, 1, v2
	v_and_or_b32 v2, v2, s0, v3
	s_movk_i32 s0, 0xc00
	v_and_b32_e32 v1, 0x78, v12
	v_mul_lo_u32 v0, v0, s0
	v_lshl_or_b32 v14, v2, 9, v4
	v_ashrrev_i32_e32 v2, 3, v6
	v_or_b32_e32 v0, v0, v1
	v_and_b32_e32 v3, 56, v12
	v_lshlrev_b32_e32 v170, 1, v0
	v_mul_lo_u32 v0, v2, s0
	v_or_b32_e32 v0, v0, v3
	s_cselect_b32 s0, 0x100, 0
	s_add_u32 s6, s39, s44
	v_lshlrev_b32_e32 v4, 7, v2
	v_lshlrev_b32_e32 v5, 1, v3
	v_lshlrev_b32_e32 v60, 1, v0
	v_lshlrev_b32_e32 v0, 3, v62
	v_and_b32_e32 v1, 0xc0, v7
	v_lshlrev_b32_e32 v2, 1, v6
	s_addc_u32 s7, s42, s43
	v_bitop3_b32 v15, v5, v4, v8 bitop3:0xde
	v_and_or_b32 v1, v0, 24, v1
	v_and_b32_e32 v2, 32, v2
	v_and_b32_e32 v0, 0x100, v0
	v_lshl_add_u64 v[4:5], s[6:7], 0, v[170:171]
	v_or3_b32 v63, v1, v2, v0
	s_add_u32 s8, s28, s44
	global_load_dwordx4 v[0:3], v170, s[6:7]
	v_add_co_u32_e32 v4, vcc, s33, v4
	s_addc_u32 s9, s29, s43
	s_nop 0
	v_addc_co_u32_e32 v5, vcc, 0, v5, vcc
	global_load_dwordx4 v[4:7], v[4:5], off
	v_add_u32_e32 v205, 0x100, v13
	global_load_dwordx4 v[8:11], v60, s[8:9]
	s_waitcnt vmcnt(3)
	ds_write_b128 v204, v[28:31] offset:51200
	ds_write_b128 v204, v[16:19] offset:52224
	ds_write_b128 v204, v[20:23] offset:53248
	ds_write_b128 v204, v[24:27] offset:54272
	s_waitcnt vmcnt(0)
	v_add_u32_e32 v206, 0x100, v14
	v_add_u32_e32 v207, 0x100, v15
	s_mov_b32 s6, s4
	s_mov_b32 s7, s4
	s_mov_b32 s8, s4
	s_mov_b32 s9, s4
	s_add_i32 s1, s38, 64
	v_add_u32_e32 v203, s0, v63
	v_lshl_add_u64 v[180:181], s[28:29], 0, v[60:61]
	s_waitcnt vmcnt(2)
	ds_write_b128 v205, v[0:3]
	v_bitop3_b32 v0, v176, v72, v73 bitop3:0xde
	v_add_u32_e32 v208, 0x100, v0
	s_waitcnt vmcnt(1)
	ds_write_b128 v206, v[4:7]
	s_waitcnt vmcnt(0)
	ds_write_b128 v207, v[8:11] offset:32768
	s_waitcnt lgkmcnt(0)
	s_barrier
	ds_read_b128 v[56:59], v204 offset:52224
	ds_read_b128 v[52:55], v204 offset:53248
	ds_read_b128 v[48:51], v204 offset:54272
	ds_read_b128 v[16:19], v208 offset:36864
	ds_read_b128 v[20:23], v208 offset:32768
	ds_read_b128 v[24:27], v204 offset:51200
	s_waitcnt lgkmcnt(0)
	v_mfma_f32_32x32x16_bf16 v[32:47], v[20:23], v[24:27], 0
	ds_read_b128 v[64:67], v209 offset:36864
	ds_read_b128 v[68:71], v209 offset:32768
	v_mov_b64_e32 v[0:1], s[4:5]
	v_mov_b64_e32 v[2:3], s[6:7]
	v_mov_b64_e32 v[4:5], s[8:9]
	v_mov_b64_e32 v[6:7], s[10:11]
	v_mov_b64_e32 v[8:9], s[12:13]
	v_mov_b64_e32 v[10:11], s[14:15]
	v_mfma_f32_32x32x16_bf16 v[16:31], v[16:19], v[24:27], 0
	v_mov_b64_e32 v[12:13], s[16:17]
	v_mov_b64_e32 v[14:15], s[18:19]
	s_add_i32 s12, s44, 0x60000
	s_mul_hi_i32 s5, s1, 0x1800
	s_add_u32 s6, s39, s12
	s_addc_u32 s7, s42, s5
	s_add_u32 s8, s28, s12
	s_waitcnt lgkmcnt(0)
	v_mfma_f32_32x32x16_bf16 v[32:47], v[68:71], v[56:59], v[32:47]
	s_addc_u32 s9, s29, s5
	s_add_i32 s1, s38, 0x80
	s_add_i32 s47, s44, 0xc0000
	s_mul_hi_i32 s46, s1, 0x1800
	v_mfma_f32_32x32x16_bf16 v[16:31], v[64:67], v[56:59], v[16:31]
	v_or_b32_e32 v56, 64, v176
	v_bitop3_b32 v56, v56, v72, v73 bitop3:0xde
	v_add_u32_e32 v210, 0x100, v56
	ds_read_b128 v[56:59], v210 offset:36864
	ds_read_b128 v[64:67], v210 offset:32768
	s_waitcnt lgkmcnt(0)
	v_mfma_f32_32x32x16_bf16 v[32:47], v[64:67], v[52:55], v[32:47]
	v_mfma_f32_32x32x16_bf16 v[16:31], v[56:59], v[52:55], v[16:31]
	v_or_b32_e32 v52, 0x60, v176
	v_bitop3_b32 v52, v52, v72, v73 bitop3:0xde
	v_add_u32_e32 v211, 0x100, v52
	ds_read_b128 v[52:55], v211 offset:36864
	ds_read_b128 v[56:59], v211 offset:32768
	s_waitcnt lgkmcnt(0)
	v_mfma_f32_32x32x16_bf16 v[32:47], v[56:59], v[48:51], v[32:47]
	v_mfma_f32_32x32x16_bf16 v[16:31], v[52:55], v[48:51], v[16:31]
	s_nop 10
	v_max_f32_e32 v48, v33, v33
	v_max_f32_e32 v49, v32, v32
	v_max_f32_e32 v48, v49, v48
	v_max3_f32 v48, v48, v34, v35
	v_max3_f32 v48, v48, v36, v37
	v_max3_f32 v48, v48, v38, v39
	v_max3_f32 v48, v48, v40, v41
	v_max3_f32 v48, v48, v42, v43
	v_max3_f32 v48, v48, v44, v45
	v_max3_f32 v48, v48, v46, v47
	v_max3_f32 v48, v48, v16, v17
	v_max3_f32 v48, v48, v18, v19
	v_max3_f32 v48, v48, v20, v21
	v_max3_f32 v48, v48, v22, v23
	v_max3_f32 v48, v48, v24, v25
	v_max3_f32 v48, v48, v26, v27
	v_max3_f32 v48, v48, v28, v29
	v_max3_f32 v48, v48, v30, v31
	v_mov_b32_e32 v49, v48
	s_nop 1
	v_permlane32_swap_b32_e32 v48, v49
	v_max_f32_e32 v49, v49, v49
	v_max_f32_e32 v48, v48, v48
	v_max_f32_e32 v48, v48, v49
	v_sub_f32_e32 v36, v36, v48
	v_sub_f32_e32 v37, v37, v48
	v_exp_f32_e32 v53, v36
	v_exp_f32_e32 v54, v37
	v_lshl_add_u64 v[36:37], s[6:7], 0, v[170:171]
	v_add_co_u32_e32 v36, vcc, s33, v36
	v_sub_f32_e32 v32, v32, v48
	v_sub_f32_e32 v33, v33, v48
	v_sub_f32_e32 v34, v34, v48
	v_sub_f32_e32 v35, v35, v48
	v_sub_f32_e32 v38, v38, v48
	v_sub_f32_e32 v39, v39, v48
	v_sub_f32_e32 v40, v40, v48
	v_sub_f32_e32 v41, v41, v48
	v_sub_f32_e32 v42, v42, v48
	v_sub_f32_e32 v43, v43, v48
	v_sub_f32_e32 v44, v44, v48
	v_sub_f32_e32 v45, v45, v48
	v_sub_f32_e32 v46, v46, v48
	v_sub_f32_e32 v47, v47, v48
	v_addc_co_u32_e32 v37, vcc, 0, v37, vcc
	v_exp_f32_e32 v49, v32
	v_exp_f32_e32 v50, v33
	v_exp_f32_e32 v51, v34
	v_exp_f32_e32 v52, v35
	v_exp_f32_e32 v55, v38
	v_exp_f32_e32 v56, v39
	v_exp_f32_e32 v57, v40
	v_exp_f32_e32 v58, v41
	v_exp_f32_e32 v59, v42
	v_exp_f32_e32 v64, v43
	v_exp_f32_e32 v65, v44
	v_exp_f32_e32 v66, v45
	v_exp_f32_e32 v46, v46
	v_exp_f32_e32 v47, v47
	v_cvt_pk_bf16_f32 v144, v49, v50
	v_cvt_pk_bf16_f32 v145, v51, v52
	v_cvt_pk_bf16_f32 v146, v53, v54
	v_cvt_pk_bf16_f32 v147, v55, v56
	v_cvt_pk_bf16_f32 v140, v57, v58
	v_cvt_pk_bf16_f32 v141, v59, v64
	v_cvt_pk_bf16_f32 v142, v65, v66
	v_cvt_pk_bf16_f32 v143, v46, v47
	global_load_dwordx4 v[32:35], v170, s[6:7]
	s_nop 0
	global_load_dwordx4 v[36:39], v[36:37], off
	s_nop 0
	global_load_dwordx4 v[40:43], v60, s[8:9]
	s_add_u32 s6, s28, s47
	s_addc_u32 s7, s29, s46
	global_load_dwordx4 v[128:131], v60, s[6:7]
	s_add_u32 s6, s39, s47
	s_addc_u32 s7, s42, s46
	v_lshl_add_u64 v[44:45], s[6:7], 0, v[170:171]
	v_add_co_u32_e32 v44, vcc, s33, v44
	v_add_f32_e32 v212, 0, v48
	s_nop 0
	v_addc_co_u32_e32 v45, vcc, 0, v45, vcc
	global_load_dwordx4 v[136:139], v[44:45], off
	global_load_dwordx4 v[132:135], v170, s[6:7]
	s_waitcnt vmcnt(3)
	s_waitcnt vmcnt(5)
	ds_write_b128 v205, v[32:35] offset:16384
	s_waitcnt vmcnt(4)
	ds_write_b128 v206, v[36:39] offset:16384
	s_waitcnt vmcnt(3)
	ds_write_b128 v207, v[40:43] offset:40960
	v_add_f32_e32 v32, 0, v49
	v_add_f32_e32 v32, v50, v32
	v_add_f32_e32 v32, v51, v32
	v_add_f32_e32 v32, v52, v32
	v_add_f32_e32 v32, v53, v32
	v_add_f32_e32 v32, v54, v32
	v_add_f32_e32 v32, v55, v32
	v_add_f32_e32 v32, v56, v32
	v_add_f32_e32 v32, v57, v32
	v_add_f32_e32 v32, v58, v32
	v_add_f32_e32 v32, v59, v32
	v_add_f32_e32 v32, v64, v32
	v_add_f32_e32 v32, v65, v32
	v_add_f32_e32 v32, v66, v32
	v_add_f32_e32 v32, v46, v32
	s_addk_i32 s0, 0x4000
	v_xor_b32_e32 v96, 0x80000000, v212
	v_add_f32_e32 v164, v47, v32
	v_sub_f32_e32 v95, v31, v48
	v_sub_f32_e32 v94, v30, v48
	v_sub_f32_e32 v93, v29, v48
	v_sub_f32_e32 v92, v28, v48
	v_sub_f32_e32 v91, v27, v48
	v_sub_f32_e32 v90, v26, v48
	v_sub_f32_e32 v89, v25, v48
	v_sub_f32_e32 v88, v24, v48
	v_sub_f32_e32 v87, v23, v48
	v_sub_f32_e32 v86, v22, v48
	v_sub_f32_e32 v85, v21, v48
	v_sub_f32_e32 v84, v20, v48
	v_sub_f32_e32 v83, v19, v48
	v_sub_f32_e32 v82, v18, v48
	v_sub_f32_e32 v81, v17, v48
	v_sub_f32_e32 v80, v16, v48
	v_add_u32_e32 v202, s0, v63
	v_mov_b64_e32 v[62:63], v[14:15]
	v_mov_b64_e32 v[46:47], v[14:15]
	v_mov_b64_e32 v[30:31], v[14:15]
	s_mov_b64 s[8:9], 0
	v_mov_b64_e32 v[60:61], v[12:13]
	v_mov_b64_e32 v[58:59], v[10:11]
	v_mov_b64_e32 v[56:57], v[8:9]
	v_mov_b64_e32 v[54:55], v[6:7]
	v_mov_b64_e32 v[52:53], v[4:5]
	v_mov_b64_e32 v[50:51], v[2:3]
	v_mov_b64_e32 v[48:49], v[0:1]
	v_mov_b64_e32 v[44:45], v[12:13]
	v_mov_b64_e32 v[42:43], v[10:11]
	v_mov_b64_e32 v[40:41], v[8:9]
	v_mov_b64_e32 v[38:39], v[6:7]
	v_mov_b64_e32 v[36:37], v[4:5]
	v_mov_b64_e32 v[34:35], v[2:3]
	v_mov_b64_e32 v[32:33], v[0:1]
	v_mov_b64_e32 v[28:29], v[12:13]
	v_mov_b64_e32 v[26:27], v[10:11]
	v_mov_b64_e32 v[24:25], v[8:9]
	v_mov_b64_e32 v[22:23], v[6:7]
	v_mov_b64_e32 v[20:21], v[4:5]
	v_mov_b64_e32 v[18:19], v[2:3]
	v_mov_b64_e32 v[16:17], v[0:1]
	v_mov_b32_e32 v97, v96
	v_mov_b32_e32 v98, v96
	v_mov_b32_e32 v99, v96
	v_mov_b32_e32 v100, v96
	v_mov_b32_e32 v101, v96
	v_mov_b32_e32 v102, v96
	v_mov_b32_e32 v103, v96
	v_mov_b32_e32 v104, v96
	v_mov_b32_e32 v105, v96
	v_mov_b32_e32 v106, v96
	v_mov_b32_e32 v107, v96
	v_mov_b32_e32 v108, v96
	v_mov_b32_e32 v109, v96
	v_mov_b32_e32 v110, v96
	v_mov_b32_e32 v111, v96
	s_waitcnt lgkmcnt(0)
	s_barrier
	s_mov_b32 s100, 0x14800
	s_mov_b32 s101, 0x18010
	v_add_u32_e32 v205, s100, v205
	v_add_u32_e32 v206, s100, v206
	v_add_u32_e32 v207, s101, v207
